# conversion split plus 4-group start skew (by bx>>6) in the GLU and out-projection phases only, where groups 1-3 have a spare round
# speedup vs baseline: 1.0043x; 1.0043x over previous
.LBB0_879:
	s_or_b64 exec, exec, s[4:5]
	v_readlane_b32 s88, v254, 10
	v_readlane_b32 s89, v254, 11
	s_waitcnt lgkmcnt(0)
	v_mov_b32_e32 v1, v0
	s_mov_b64 s[0:1], s[88:89]
	s_barrier
	s_load_dwordx2 s[8:9], s[0:1], 0xd0
	s_load_dwordx2 s[4:5], s[0:1], 0x108
	v_readlane_b32 s99, v254, 12
	s_nop 3
	s_lshr_b32 s99, s99, 6
	s_mul_i32 s99, s99, 300
	s_add_i32 s100, s99, -1
	s_cmp_lg_u32 s99, 0
	s_cselect_b64 vcc, -1, 0
	v_readlane_b32 s62, v254, 24
	v_readlane_b32 s63, v254, 25
	s_cbranch_vccz .LBB0_883
	s_memrealtime s[0:1]
	s_memrealtime s[2:3]
	v_mov_b32_e32 v2, s100
	v_mov_b32_e32 v3, 0
	s_waitcnt lgkmcnt(0)
	s_sub_u32 s2, s2, s0
	s_subb_u32 s3, s3, s1
	v_cmp_gt_u64_e32 vcc, s[2:3], v[2:3]
	s_cbranch_vccnz .LBB0_883
	v_mov_b32_e32 v2, s99
	v_mov_b32_e32 v3, 0

.LBB0_952:
	s_or_b64 exec, exec, s[4:5]
	s_waitcnt lgkmcnt(0)
	v_mov_b32_e32 v1, v0
	s_mov_b64 s[0:1], s[88:89]
	s_barrier
	s_load_dwordx2 s[12:13], s[0:1], 0x108
	s_load_dwordx4 s[8:11], s[0:1], 0x0
	s_load_dwordx2 s[14:15], s[0:1], 0xe0
	v_readfirstlane_b32 s2, v1
	v_readlane_b32 s99, v254, 12
	s_nop 3
	s_lshr_b32 s99, s99, 6
	s_mul_i32 s99, s99, 750
	s_add_i32 s100, s99, -1
	s_cmp_lg_u32 s99, 0
	s_cselect_b64 vcc, -1, 0
	s_cbranch_vccz .LBB0_956
	s_memrealtime s[0:1]
	s_memrealtime s[4:5]
	v_mov_b32_e32 v2, s100
	v_mov_b32_e32 v3, 0
	s_waitcnt lgkmcnt(0)
	s_sub_u32 s4, s4, s0
	s_subb_u32 s5, s5, s1
	v_cmp_gt_u64_e32 vcc, s[4:5], v[2:3]
	s_cbranch_vccnz .LBB0_956
	v_mov_b32_e32 v2, s99
	v_mov_b32_e32 v3, 0
